# attention: three xor-32 cross-half sums per unit (q norm, row sum l, sub-layer norm ss) via v_permlane32_swap instead of ds_bpermute
# baseline (speedup 1.0000x reference)
.LBB0_520:
	v_mov_b32_e32 v218, v3
	s_and_b32 s56, s60, 0xffffff80
	s_sub_i32 s79, s66, s56
	s_lshl_b32 s4, s60, 8
	v_add_u32_e32 v184, s79, v198
	s_and_b32 s8, s4, 0x7800
	v_ashrrev_i32_e32 v185, 31, v184
	v_lshl_add_u64 v[182:183], v[184:185], 0, s[8:9]
	s_and_b32 s78, s60, 7
	v_lshlrev_b64 v[4:5], 11, v[182:183]
	v_lshl_add_u64 v[4:5], s[38:39], 0, v[4:5]
	s_lshl_b32 s4, s78, 8
	s_mov_b32 s5, s9
	v_lshl_add_u64 v[4:5], v[4:5], 0, s[4:5]
	v_lshl_add_u64 v[4:5], v[4:5], 0, s[14:15]
	v_mov_b32_e32 v179, v3
	v_lshl_add_u64 v[4:5], v[4:5], 0, v[178:179]
	global_load_dwordx4 v[114:117], v[4:5], off
	global_load_dwordx4 v[118:121], v[4:5], off offset:32
	global_load_dwordx4 v[122:125], v[4:5], off offset:64
	global_load_dwordx4 v[126:129], v[4:5], off offset:96
	s_add_i32 s5, s78, 1
	s_ashr_i32 s57, s60, 6
	v_cvt_f32_ubyte0_e32 v18, s5
	s_and_b32 s58, s57, -2
	v_cmp_lt_f32_e32 vcc, s72, v18
	s_and_b64 s[60:61], vcc, exec
	s_cselect_b32 s59, 0xffffffc0, 0
	s_lshl_b32 s5, s8, 11
	s_add_u32 s8, s63, s5
	s_addc_u32 s61, s64, 0
	s_add_u32 s60, s8, s4
	s_addc_u32 s61, s61, 0
	s_mov_b64 s[100:101], s[60:61]
	s_add_u32 s5, s65, s5
	s_addc_u32 s8, s70, 0
	s_add_u32 s4, s5, s4
	s_addc_u32 s5, s8, 0
	s_sub_i32 s8, 31, s58
	v_mov_b32_e32 v181, v3
	v_lshl_or_b32 v2, s8, 6, v199
	v_lshl_add_u64 v[186:187], s[60:61], 0, v[180:181]
	v_lshlrev_b64 v[6:7], 11, v[2:3]
	s_lshl_b32 s60, s58, 6
	v_lshl_add_u64 v[8:9], v[186:187], 0, v[6:7]
	v_cndmask_b32_e32 v19, 0, v215, vcc
	v_lshl_add_u64 v[188:189], s[4:5], 0, v[180:181]
	v_subrev_u32_e32 v4, s60, v199
	v_add_co_u32_e32 v12, vcc, s73, v8
	v_add_u32_e32 v2, 0x780, v4
	v_lshl_add_u64 v[6:7], v[188:189], 0, v[6:7]
	v_addc_co_u32_e32 v13, vcc, 0, v9, vcc
	v_lshlrev_b64 v[10:11], 11, v[2:3]
	v_add_co_u32_e32 v14, vcc, s73, v6
	v_lshl_add_u64 v[16:17], v[186:187], 0, v[10:11]
	s_nop 0
	v_addc_co_u32_e32 v15, vcc, 0, v7, vcc
	global_load_dwordx4 v[134:137], v[8:9], off
	global_load_dwordx4 v[154:157], v[12:13], off
	global_load_dwordx4 v[146:149], v[6:7], off
	global_load_dwordx4 v[158:161], v[14:15], off
	v_add_co_u32_e32 v6, vcc, s73, v16
	v_lshl_add_u64 v[10:11], v[188:189], 0, v[10:11]
	s_nop 0
	v_addc_co_u32_e32 v7, vcc, 0, v17, vcc
	v_add_co_u32_e32 v8, vcc, s73, v10
	s_waitcnt vmcnt(7)
	v_and_b32_e32 v5, 0xffff0000, v114
	v_lshlrev_b32_e32 v2, 16, v114
	v_mul_f32_e32 v5, v5, v5
	v_addc_co_u32_e32 v9, vcc, 0, v11, vcc
	global_load_dwordx4 v[130:133], v[16:17], off
	global_load_dwordx4 v[142:145], v[6:7], off
	global_load_dwordx4 v[138:141], v[10:11], off
	global_load_dwordx4 v[150:153], v[8:9], off
	v_lshlrev_b32_e32 v6, 16, v115
	v_fmac_f32_e32 v5, v2, v2
	v_and_b32_e32 v7, 0xffff0000, v115
	v_fmac_f32_e32 v5, v6, v6
	v_lshlrev_b32_e32 v8, 16, v116
	v_fmac_f32_e32 v5, v7, v7
	v_and_b32_e32 v9, 0xffff0000, v116
	v_fmac_f32_e32 v5, v8, v8
	v_lshlrev_b32_e32 v10, 16, v117
	v_fmac_f32_e32 v5, v9, v9
	v_and_b32_e32 v11, 0xffff0000, v117
	v_fmac_f32_e32 v5, v10, v10
	s_waitcnt vmcnt(10)
	v_lshlrev_b32_e32 v12, 16, v118
	v_fmac_f32_e32 v5, v11, v11
	v_and_b32_e32 v13, 0xffff0000, v118
	v_fmac_f32_e32 v5, v12, v12
	v_lshlrev_b32_e32 v14, 16, v119
	v_fmac_f32_e32 v5, v13, v13
	v_and_b32_e32 v15, 0xffff0000, v119
	v_fmac_f32_e32 v5, v14, v14
	v_lshlrev_b32_e32 v16, 16, v120
	v_fmac_f32_e32 v5, v15, v15
	v_and_b32_e32 v17, 0xffff0000, v120
	v_fmac_f32_e32 v5, v16, v16
	v_lshlrev_b32_e32 v20, 16, v121
	v_fmac_f32_e32 v5, v17, v17
	v_and_b32_e32 v21, 0xffff0000, v121
	v_fmac_f32_e32 v5, v20, v20
	v_fmac_f32_e32 v5, v21, v21
	s_waitcnt vmcnt(9)
	v_lshlrev_b32_e32 v2, 16, v122
	v_fmac_f32_e32 v5, v2, v2
	v_and_b32_e32 v2, 0xffff0000, v122
	v_fmac_f32_e32 v5, v2, v2
	v_lshlrev_b32_e32 v2, 16, v123
	v_fmac_f32_e32 v5, v2, v2
	v_and_b32_e32 v2, 0xffff0000, v123
	v_fmac_f32_e32 v5, v2, v2
	v_lshlrev_b32_e32 v2, 16, v124
	v_fmac_f32_e32 v5, v2, v2
	v_and_b32_e32 v2, 0xffff0000, v124
	v_fmac_f32_e32 v5, v2, v2
	v_lshlrev_b32_e32 v2, 16, v125
	v_fmac_f32_e32 v5, v2, v2
	v_and_b32_e32 v2, 0xffff0000, v125
	v_fmac_f32_e32 v5, v2, v2
	s_waitcnt vmcnt(8)
	v_lshlrev_b32_e32 v2, 16, v126
	v_fmac_f32_e32 v5, v2, v2
	v_and_b32_e32 v2, 0xffff0000, v126
	v_fmac_f32_e32 v5, v2, v2
	v_lshlrev_b32_e32 v2, 16, v127
	v_fmac_f32_e32 v5, v2, v2
	v_and_b32_e32 v2, 0xffff0000, v127
	v_fmac_f32_e32 v5, v2, v2
	v_lshlrev_b32_e32 v2, 16, v128
	v_fmac_f32_e32 v5, v2, v2
	v_and_b32_e32 v2, 0xffff0000, v128
	v_fmac_f32_e32 v5, v2, v2
	v_lshlrev_b32_e32 v2, 16, v129
	v_fmac_f32_e32 v5, v2, v2
	v_and_b32_e32 v2, 0xffff0000, v129
	v_fmac_f32_e32 v5, v2, v2
	v_mov_b32_e32 v2, v5
	v_sub_f32_e32 v6, v19, v18
	v_exp_f32_e32 v6, v6
	v_permlane32_swap_b32_e32 v2, v5
	v_add_f32_e32 v2, v5, v2
	v_mul_f32_e32 v5, 0x4f800000, v2
	v_cmp_gt_f32_e32 vcc, s71, v2
	v_ldexp_f32 v6, v6, s59
	v_mul_f32_e32 v190, 0x3fb8aa3b, v6
	v_cndmask_b32_e32 v2, v2, v5, vcc
	v_sqrt_f32_e32 v5, v2
	s_nop 0
	v_add_u32_e32 v6, -1, v5
	v_fma_f32 v7, -v6, v5, v2
	v_cmp_ge_f32_e64 s[4:5], 0, v7
	v_add_u32_e32 v7, 1, v5
	s_nop 0
	v_cndmask_b32_e64 v6, v5, v6, s[4:5]
	v_fma_f32 v5, -v7, v5, v2
	v_cmp_lt_f32_e64 s[4:5], 0, v5
	s_nop 1
	v_cndmask_b32_e64 v5, v6, v7, s[4:5]
	v_mul_f32_e32 v6, 0x37800000, v5
	v_cndmask_b32_e32 v5, v5, v6, vcc
	v_cmp_class_f32_e32 vcc, v2, v200
	s_nop 1
	v_cndmask_b32_e32 v2, v5, v2, vcc
	v_mul_f32_e32 v5, v201, v2
	v_fmaak_f32 v2, 2.0, v5, 0x42200000
	v_div_scale_f32 v6, s[4:5], v190, v190, v2
	v_rcp_f32_e32 v7, v6
	s_nop 0
	v_fma_f32 v8, -v6, v7, 1.0
	v_fmac_f32_e32 v7, v8, v7
	v_div_scale_f32 v8, vcc, v2, v190, v2
	v_mul_f32_e32 v9, v8, v7
	v_fma_f32 v10, -v6, v9, v8
	v_fmac_f32_e32 v9, v10, v7
	v_fma_f32 v6, -v6, v9, v8
	v_div_fmas_f32 v6, v6, v7, v9
	v_div_fixup_f32 v2, v6, v190, v2
	s_nop 1
	v_max_f32_dpp v2, v2, v2 quad_perm:[1,0,3,2] row_mask:0xf bank_mask:0xf
	s_nop 1
	v_max_f32_dpp v2, v2, v2 quad_perm:[2,3,0,1] row_mask:0xf bank_mask:0xf
	s_nop 1
	v_max_f32_dpp v2, v2, v2 row_half_mirror row_mask:0xf bank_mask:0xf
	s_nop 1
	v_max_f32_dpp v2, v2, v2 row_mirror row_mask:0xf bank_mask:0xf
	s_nop 1
	v_max_f32_dpp v2, v2, v2 row_bcast:15 row_mask:0xa bank_mask:0xf
	s_nop 1
	v_readlane_b32 s98, v2, 31
	s_and_saveexec_b64 s[4:5], s[0:1]
	s_cbranch_execz .LBB0_526
	s_nop 0
	v_mov_b32_e32 v2, s98
	v_mov_b32_e32 v6, s67
	ds_write_b32 v6, v2

.Lmy_epi_noload:
	v_mov_b32_e32 v2, v168
	v_lshlrev_b64 v[4:5], 10, v[182:183]
	s_lshl_b32 s4, s78, 7
	s_nop 0
	v_permlane32_swap_b32_e32 v2, v168
	v_add_f32_e32 v2, v168, v2
	v_div_scale_f32 v6, s[56:57], v2, v2, 1.0
	v_rcp_f32_e32 v7, v6
	v_div_scale_f32 v8, vcc, 1.0, v2, 1.0
	v_fma_f32 v9, -v6, v7, 1.0
	v_fmac_f32_e32 v7, v9, v7
	v_mul_f32_e32 v9, v8, v7
	v_fma_f32 v10, -v6, v9, v8
	v_fmac_f32_e32 v9, v10, v7
	v_fma_f32 v6, -v6, v9, v8
	v_div_fmas_f32 v6, v6, v7, v9
	s_andn2_b64 vcc, exec, s[12:13]
	v_div_fixup_f32 v6, v6, v2, 1.0
	s_cbranch_vccnz .LBB0_561
	v_mul_f32_e32 v2, v66, v6
	v_mul_f32_e32 v7, v67, v6
	ds_write2st64_b32 v211, v2, v7 offset1:1
	v_mul_f32_e32 v2, v68, v6
	v_mul_f32_e32 v7, v69, v6
	ds_write2st64_b32 v211, v2, v7 offset0:2 offset1:3
	v_mul_f32_e32 v2, v70, v6
	v_mul_f32_e32 v7, v71, v6
	ds_write2st64_b32 v211, v2, v7 offset0:4 offset1:5
	v_mul_f32_e32 v2, v72, v6
	v_mul_f32_e32 v7, v73, v6
	ds_write2st64_b32 v211, v2, v7 offset0:6 offset1:7
	v_mul_f32_e32 v2, v74, v6
	v_mul_f32_e32 v7, v75, v6
	ds_write2st64_b32 v211, v2, v7 offset0:8 offset1:9
	v_mul_f32_e32 v2, v76, v6
	v_mul_f32_e32 v7, v77, v6
	ds_write2st64_b32 v211, v2, v7 offset0:10 offset1:11
	v_mul_f32_e32 v2, v78, v6
	v_mul_f32_e32 v7, v79, v6
	ds_write2st64_b32 v211, v2, v7 offset0:12 offset1:13
	v_mul_f32_e32 v2, v80, v6
	v_mul_f32_e32 v7, v81, v6
	ds_write2st64_b32 v211, v2, v7 offset0:14 offset1:15
	v_mul_f32_e32 v2, v50, v6
	v_mul_f32_e32 v7, v51, v6
	ds_write2st64_b32 v211, v2, v7 offset0:16 offset1:17
	v_mul_f32_e32 v2, v52, v6
	v_mul_f32_e32 v7, v53, v6
	ds_write2st64_b32 v211, v2, v7 offset0:18 offset1:19
	v_mul_f32_e32 v2, v54, v6
	v_mul_f32_e32 v7, v55, v6
	ds_write2st64_b32 v211, v2, v7 offset0:20 offset1:21
	v_mul_f32_e32 v2, v56, v6
	v_mul_f32_e32 v7, v57, v6
	ds_write2st64_b32 v211, v2, v7 offset0:22 offset1:23
	v_mul_f32_e32 v2, v58, v6
	v_mul_f32_e32 v7, v59, v6
	ds_write2st64_b32 v211, v2, v7 offset0:24 offset1:25
	v_mul_f32_e32 v2, v60, v6
	v_mul_f32_e32 v7, v61, v6
	ds_write2st64_b32 v211, v2, v7 offset0:26 offset1:27
	v_mul_f32_e32 v2, v62, v6
	v_mul_f32_e32 v7, v63, v6
	ds_write2st64_b32 v211, v2, v7 offset0:28 offset1:29
	v_mul_f32_e32 v2, v64, v6
	v_mul_f32_e32 v7, v65, v6
	ds_write2st64_b32 v211, v2, v7 offset0:30 offset1:31
	v_mul_f32_e32 v2, v34, v6
	v_mul_f32_e32 v7, v35, v6
	ds_write2st64_b32 v211, v2, v7 offset0:32 offset1:33
	v_mul_f32_e32 v2, v36, v6
	v_mul_f32_e32 v7, v37, v6
	ds_write2st64_b32 v211, v2, v7 offset0:34 offset1:35
	v_mul_f32_e32 v2, v38, v6
	v_mul_f32_e32 v7, v39, v6
	ds_write2st64_b32 v211, v2, v7 offset0:36 offset1:37
	v_mul_f32_e32 v2, v40, v6
	v_mul_f32_e32 v7, v41, v6
	ds_write2st64_b32 v211, v2, v7 offset0:38 offset1:39
	v_mul_f32_e32 v2, v42, v6
	v_mul_f32_e32 v7, v43, v6
	ds_write2st64_b32 v211, v2, v7 offset0:40 offset1:41
	v_mul_f32_e32 v2, v44, v6
	v_mul_f32_e32 v7, v45, v6
	ds_write2st64_b32 v211, v2, v7 offset0:42 offset1:43
	v_mul_f32_e32 v2, v46, v6
	v_mul_f32_e32 v7, v47, v6
	ds_write2st64_b32 v211, v2, v7 offset0:44 offset1:45
	v_mul_f32_e32 v2, v48, v6
	v_mul_f32_e32 v7, v49, v6
	ds_write2st64_b32 v211, v2, v7 offset0:46 offset1:47
	v_mul_f32_e32 v2, v18, v6
	v_mul_f32_e32 v7, v19, v6
	ds_write2st64_b32 v211, v2, v7 offset0:48 offset1:49
	v_mul_f32_e32 v2, v20, v6
	v_mul_f32_e32 v7, v21, v6
	ds_write2st64_b32 v211, v2, v7 offset0:50 offset1:51
	v_mul_f32_e32 v2, v22, v6
	v_mul_f32_e32 v7, v23, v6
	ds_write2st64_b32 v211, v2, v7 offset0:52 offset1:53
	v_mul_f32_e32 v2, v24, v6
	v_mul_f32_e32 v7, v25, v6
	ds_write2st64_b32 v211, v2, v7 offset0:54 offset1:55
	v_mul_f32_e32 v2, v26, v6
	v_mul_f32_e32 v7, v27, v6
	ds_write2st64_b32 v211, v2, v7 offset0:56 offset1:57
	v_mul_f32_e32 v2, v28, v6
	v_mul_f32_e32 v7, v29, v6
	ds_write2st64_b32 v211, v2, v7 offset0:58 offset1:59
	v_mul_f32_e32 v2, v30, v6
	v_mul_f32_e32 v7, v31, v6
	ds_write2st64_b32 v211, v2, v7 offset0:60 offset1:61
	v_mul_f32_e32 v2, v32, v6
	v_mul_f32_e32 v7, v33, v6
	ds_write2st64_b32 v211, v2, v7 offset0:62 offset1:63
.LBB0_561:
	s_andn2_b64 vcc, exec, s[10:11]
	s_waitcnt lgkmcnt(0)
	s_barrier
	s_cbranch_vccnz .LBB0_563
	ds_read2st64_b32 v[8:9], v211 offset1:1
	ds_read2st64_b32 v[10:11], v211 offset0:2 offset1:3
	ds_read2st64_b32 v[16:17], v211 offset0:4 offset1:5
	ds_read2st64_b32 v[82:83], v211 offset0:6 offset1:7
	v_mov_b32_e32 v168, v66
	v_or_b32_e32 v4, s4, v4
	s_waitcnt lgkmcnt(3)
	v_mov_b32_e32 v7, v8
	v_pk_mul_f32 v[12:13], v[168:169], v[6:7]
	v_mov_b32_e32 v168, v67
	v_mov_b32_e32 v7, v9
	v_pk_mul_f32 v[8:9], v[168:169], v[6:7]
	v_mov_b32_e32 v168, v68
	s_waitcnt lgkmcnt(2)
	v_mov_b32_e32 v7, v10
	v_sub_f32_e32 v14, v8, v9
	v_pk_mul_f32 v[8:9], v[168:169], v[6:7]
	v_mov_b32_e32 v168, v69
	v_mov_b32_e32 v7, v11
	v_pk_mul_f32 v[10:11], v[168:169], v[6:7]
	v_mov_b32_e32 v168, v70
	s_waitcnt lgkmcnt(1)
	v_mov_b32_e32 v7, v16
	v_sub_f32_e32 v8, v8, v9
	v_sub_f32_e32 v9, v10, v11
	v_pk_mul_f32 v[10:11], v[168:169], v[6:7]
	v_mov_b32_e32 v168, v71
	v_mov_b32_e32 v7, v17
	v_sub_f32_e32 v2, v10, v11
	v_pk_mul_f32 v[10:11], v[168:169], v[6:7]
	v_mov_b32_e32 v168, v72
	s_waitcnt lgkmcnt(0)
	v_mov_b32_e32 v7, v82
	v_pk_mul_f32 v[16:17], v[168:169], v[6:7]
	v_mov_b32_e32 v168, v73
	v_mov_b32_e32 v7, v83
	v_sub_f32_e32 v10, v10, v11
	v_sub_f32_e32 v11, v16, v17
	v_pk_mul_f32 v[16:17], v[168:169], v[6:7]
	v_sub_f32_e32 v13, v12, v13
	v_sub_f32_e32 v12, v16, v17
	ds_read2st64_b32 v[16:17], v211 offset0:8 offset1:9
	ds_read2st64_b32 v[72:73], v211 offset0:10 offset1:11
	ds_read2st64_b32 v[82:83], v211 offset0:12 offset1:13
	ds_read2st64_b32 v[84:85], v211 offset0:14 offset1:15
	v_mov_b32_e32 v168, v74
	s_waitcnt lgkmcnt(3)
	v_mov_b32_e32 v7, v16
	v_pk_mul_f32 v[66:67], v[168:169], v[6:7]
	v_mov_b32_e32 v168, v75
	v_mov_b32_e32 v7, v17
	v_pk_mul_f32 v[16:17], v[168:169], v[6:7]
	v_mov_b32_e32 v168, v76
	s_waitcnt lgkmcnt(2)
	v_mov_b32_e32 v7, v72
	v_sub_f32_e32 v70, v16, v17
	v_pk_mul_f32 v[16:17], v[168:169], v[6:7]
	v_mov_b32_e32 v168, v77
	v_mov_b32_e32 v7, v73
	ds_read2st64_b32 v[74:75], v211 offset0:16 offset1:17
	v_sub_f32_e32 v69, v66, v67
	v_sub_f32_e32 v67, v16, v17
	v_pk_mul_f32 v[16:17], v[168:169], v[6:7]
	v_mov_b32_e32 v168, v78
	s_waitcnt lgkmcnt(2)
	v_mov_b32_e32 v7, v82
	v_sub_f32_e32 v68, v16, v17
	v_pk_mul_f32 v[16:17], v[168:169], v[6:7]
	v_mov_b32_e32 v168, v79
	v_mov_b32_e32 v7, v83
	v_sub_f32_e32 v15, v16, v17
	v_pk_mul_f32 v[16:17], v[168:169], v[6:7]
	v_mov_b32_e32 v168, v80
	s_waitcnt lgkmcnt(1)
	v_mov_b32_e32 v7, v84
	v_pk_mul_f32 v[72:73], v[168:169], v[6:7]
	v_mov_b32_e32 v168, v81
	v_mov_b32_e32 v7, v85
	ds_read2st64_b32 v[76:77], v211 offset0:18 offset1:19
	ds_read2st64_b32 v[78:79], v211 offset0:20 offset1:21
	ds_read2st64_b32 v[80:81], v211 offset0:22 offset1:23
	v_sub_f32_e32 v16, v16, v17
	v_sub_f32_e32 v17, v72, v73
	v_pk_mul_f32 v[72:73], v[168:169], v[6:7]
	v_mov_b32_e32 v168, v50
	s_waitcnt lgkmcnt(3)
	v_mov_b32_e32 v7, v74
	v_sub_f32_e32 v66, v72, v73
	v_pk_mul_f32 v[72:73], v[168:169], v[6:7]
	v_mov_b32_e32 v168, v51
	v_mov_b32_e32 v7, v75
	v_pk_mul_f32 v[50:51], v[168:169], v[6:7]
	v_mov_b32_e32 v168, v52
	s_waitcnt lgkmcnt(2)
	v_mov_b32_e32 v7, v76
	v_sub_f32_e32 v74, v50, v51
	v_pk_mul_f32 v[50:51], v[168:169], v[6:7]
	v_mov_b32_e32 v168, v53
	v_mov_b32_e32 v7, v77
	v_sub_f32_e32 v71, v50, v51
	v_pk_mul_f32 v[50:51], v[168:169], v[6:7]
	v_mov_b32_e32 v168, v54
	s_waitcnt lgkmcnt(1)
	v_mov_b32_e32 v7, v78
	v_sub_f32_e32 v73, v72, v73
	v_sub_f32_e32 v72, v50, v51
	v_pk_mul_f32 v[50:51], v[168:169], v[6:7]
	v_mov_b32_e32 v168, v55
	v_mov_b32_e32 v7, v79
	v_pk_mul_f32 v[52:53], v[168:169], v[6:7]
	v_mov_b32_e32 v168, v56
	s_waitcnt lgkmcnt(0)
	v_mov_b32_e32 v7, v80
	v_sub_f32_e32 v50, v50, v51
	v_sub_f32_e32 v51, v52, v53
	v_pk_mul_f32 v[52:53], v[168:169], v[6:7]
	v_mov_b32_e32 v168, v57
	v_mov_b32_e32 v7, v81
	v_pk_mul_f32 v[54:55], v[168:169], v[6:7]
	v_sub_f32_e32 v52, v52, v53
	v_sub_f32_e32 v53, v54, v55
	ds_read2st64_b32 v[54:55], v211 offset0:24 offset1:25
	ds_read2st64_b32 v[56:57], v211 offset0:26 offset1:27
	ds_read2st64_b32 v[78:79], v211 offset0:28 offset1:29
	ds_read2st64_b32 v[80:81], v211 offset0:30 offset1:31
	v_mov_b32_e32 v168, v58
	s_waitcnt lgkmcnt(3)
	v_mov_b32_e32 v7, v54
	v_pk_mul_f32 v[76:77], v[168:169], v[6:7]
	v_mov_b32_e32 v168, v59
	v_mov_b32_e32 v7, v55
	v_pk_mul_f32 v[54:55], v[168:169], v[6:7]
	v_mov_b32_e32 v168, v60
	s_waitcnt lgkmcnt(2)
	v_mov_b32_e32 v7, v56
	v_sub_f32_e32 v75, v76, v77
	v_sub_f32_e32 v76, v54, v55
	v_pk_mul_f32 v[54:55], v[168:169], v[6:7]
	v_mov_b32_e32 v168, v61
	v_mov_b32_e32 v7, v57
	v_sub_f32_e32 v58, v54, v55
	v_pk_mul_f32 v[54:55], v[168:169], v[6:7]
	v_mov_b32_e32 v168, v62
	s_waitcnt lgkmcnt(1)
	v_mov_b32_e32 v7, v78
	v_sub_f32_e32 v59, v54, v55
	v_pk_mul_f32 v[54:55], v[168:169], v[6:7]
	v_mov_b32_e32 v168, v63
	v_mov_b32_e32 v7, v79
	v_pk_mul_f32 v[56:57], v[168:169], v[6:7]
	v_mov_b32_e32 v168, v64
	s_waitcnt lgkmcnt(0)
	v_mov_b32_e32 v7, v80
	v_sub_f32_e32 v54, v54, v55
	v_sub_f32_e32 v55, v56, v57
	v_pk_mul_f32 v[56:57], v[168:169], v[6:7]
	v_mov_b32_e32 v168, v65
	v_mov_b32_e32 v7, v81
	v_pk_mul_f32 v[60:61], v[168:169], v[6:7]
	v_sub_f32_e32 v56, v56, v57
	v_sub_f32_e32 v57, v60, v61
	ds_read2st64_b32 v[60:61], v211 offset0:32 offset1:33
	ds_read2st64_b32 v[64:65], v211 offset0:34 offset1:35
	ds_read2st64_b32 v[78:79], v211 offset0:36 offset1:37
	ds_read2st64_b32 v[80:81], v211 offset0:38 offset1:39
	v_mov_b32_e32 v168, v34
	v_mul_f32_e32 v77, v13, v13
	v_fmac_f32_e32 v77, v14, v14
	s_waitcnt lgkmcnt(3)
	v_mov_b32_e32 v7, v60
	v_pk_mul_f32 v[62:63], v[168:169], v[6:7]
	v_mov_b32_e32 v168, v35
	v_mov_b32_e32 v7, v61
	v_pk_mul_f32 v[34:35], v[168:169], v[6:7]
	v_mov_b32_e32 v168, v36
	s_waitcnt lgkmcnt(2)
	v_mov_b32_e32 v7, v64
	v_sub_f32_e32 v62, v62, v63
	v_sub_f32_e32 v63, v34, v35
	v_pk_mul_f32 v[34:35], v[168:169], v[6:7]
	v_mov_b32_e32 v168, v37
	v_mov_b32_e32 v7, v65
	v_sub_f32_e32 v60, v34, v35
	v_pk_mul_f32 v[34:35], v[168:169], v[6:7]
	v_mov_b32_e32 v168, v38
	s_waitcnt lgkmcnt(1)
	v_mov_b32_e32 v7, v78
	v_sub_f32_e32 v61, v34, v35
	v_pk_mul_f32 v[34:35], v[168:169], v[6:7]
	v_mov_b32_e32 v168, v39
	v_mov_b32_e32 v7, v79
	v_pk_mul_f32 v[36:37], v[168:169], v[6:7]
	v_mov_b32_e32 v168, v40
	s_waitcnt lgkmcnt(0)
	v_mov_b32_e32 v7, v80
	v_sub_f32_e32 v34, v34, v35
	v_sub_f32_e32 v35, v36, v37
	v_pk_mul_f32 v[36:37], v[168:169], v[6:7]
	v_mov_b32_e32 v168, v41
	v_mov_b32_e32 v7, v81
	v_pk_mul_f32 v[38:39], v[168:169], v[6:7]
	v_sub_f32_e32 v36, v36, v37
	v_sub_f32_e32 v37, v38, v39
	ds_read2st64_b32 v[38:39], v211 offset0:40 offset1:41
	ds_read2st64_b32 v[40:41], v211 offset0:42 offset1:43
	ds_read2st64_b32 v[78:79], v211 offset0:44 offset1:45
	ds_read2st64_b32 v[80:81], v211 offset0:46 offset1:47
	v_mov_b32_e32 v168, v42
	v_fmac_f32_e32 v77, v8, v8
	v_fmac_f32_e32 v77, v9, v9
	s_waitcnt lgkmcnt(3)
	v_mov_b32_e32 v7, v38
	v_pk_mul_f32 v[64:65], v[168:169], v[6:7]
	v_mov_b32_e32 v168, v43
	v_mov_b32_e32 v7, v39
	v_pk_mul_f32 v[38:39], v[168:169], v[6:7]
	v_mov_b32_e32 v168, v44
	s_waitcnt lgkmcnt(2)
	v_mov_b32_e32 v7, v40
	v_sub_f32_e32 v64, v64, v65
	v_sub_f32_e32 v65, v38, v39
	v_pk_mul_f32 v[38:39], v[168:169], v[6:7]
	v_mov_b32_e32 v168, v45
	v_mov_b32_e32 v7, v41
	v_sub_f32_e32 v42, v38, v39
	v_pk_mul_f32 v[38:39], v[168:169], v[6:7]
	v_mov_b32_e32 v168, v46
	s_waitcnt lgkmcnt(1)
	v_mov_b32_e32 v7, v78
	v_sub_f32_e32 v43, v38, v39
	v_pk_mul_f32 v[38:39], v[168:169], v[6:7]
	v_mov_b32_e32 v168, v47
	v_mov_b32_e32 v7, v79
	v_pk_mul_f32 v[40:41], v[168:169], v[6:7]
	v_mov_b32_e32 v168, v48
	s_waitcnt lgkmcnt(0)
	v_mov_b32_e32 v7, v80
	v_sub_f32_e32 v38, v38, v39
	v_sub_f32_e32 v39, v40, v41
	v_pk_mul_f32 v[40:41], v[168:169], v[6:7]
	v_mov_b32_e32 v168, v49
	v_mov_b32_e32 v7, v81
	v_pk_mul_f32 v[44:45], v[168:169], v[6:7]
	v_sub_f32_e32 v40, v40, v41
	v_sub_f32_e32 v41, v44, v45
	ds_read2st64_b32 v[44:45], v211 offset0:48 offset1:49
	ds_read2st64_b32 v[48:49], v211 offset0:50 offset1:51
	ds_read2st64_b32 v[78:79], v211 offset0:52 offset1:53
	ds_read2st64_b32 v[80:81], v211 offset0:54 offset1:55
	v_mov_b32_e32 v168, v18
	v_fmac_f32_e32 v77, v2, v2
	v_fmac_f32_e32 v77, v10, v10
	s_waitcnt lgkmcnt(3)
	v_mov_b32_e32 v7, v44
	v_pk_mul_f32 v[46:47], v[168:169], v[6:7]
	v_mov_b32_e32 v168, v19
	v_mov_b32_e32 v7, v45
	v_pk_mul_f32 v[18:19], v[168:169], v[6:7]
	v_mov_b32_e32 v168, v20
	s_waitcnt lgkmcnt(2)
	v_mov_b32_e32 v7, v48
	v_sub_f32_e32 v46, v46, v47
	v_sub_f32_e32 v47, v18, v19
	v_pk_mul_f32 v[18:19], v[168:169], v[6:7]
	v_mov_b32_e32 v168, v21
	v_mov_b32_e32 v7, v49
	v_sub_f32_e32 v44, v18, v19
	v_pk_mul_f32 v[18:19], v[168:169], v[6:7]
	v_mov_b32_e32 v168, v22
	s_waitcnt lgkmcnt(1)
	v_mov_b32_e32 v7, v78
	v_sub_f32_e32 v45, v18, v19
	v_pk_mul_f32 v[18:19], v[168:169], v[6:7]
	v_mov_b32_e32 v168, v23
	v_mov_b32_e32 v7, v79
	v_pk_mul_f32 v[20:21], v[168:169], v[6:7]
	v_mov_b32_e32 v168, v24
	s_waitcnt lgkmcnt(0)
	v_mov_b32_e32 v7, v80
	v_sub_f32_e32 v18, v18, v19
	v_sub_f32_e32 v19, v20, v21
	v_pk_mul_f32 v[20:21], v[168:169], v[6:7]
	v_mov_b32_e32 v168, v25
	v_mov_b32_e32 v7, v81
	v_pk_mul_f32 v[22:23], v[168:169], v[6:7]
	v_fmac_f32_e32 v77, v11, v11
	v_sub_f32_e32 v20, v20, v21
	v_sub_f32_e32 v21, v22, v23
	ds_read2st64_b32 v[22:23], v211 offset0:56 offset1:57
	v_fmac_f32_e32 v77, v12, v12
	v_fmac_f32_e32 v77, v69, v69
	v_fmac_f32_e32 v77, v70, v70
	v_fmac_f32_e32 v77, v67, v67
	ds_read2st64_b32 v[24:25], v211 offset0:58 offset1:59
	ds_read2st64_b32 v[48:49], v211 offset0:60 offset1:61
	ds_read2st64_b32 v[78:79], v211 offset0:62 offset1:63
	v_fmac_f32_e32 v77, v68, v68
	v_mov_b32_e32 v168, v26
	s_waitcnt lgkmcnt(3)
	v_mov_b32_e32 v7, v22
	v_fmac_f32_e32 v77, v15, v15
	v_pk_mul_f32 v[80:81], v[168:169], v[6:7]
	v_mov_b32_e32 v168, v27
	v_mov_b32_e32 v7, v23
	v_fmac_f32_e32 v77, v16, v16
	v_pk_mul_f32 v[22:23], v[168:169], v[6:7]
	v_mov_b32_e32 v168, v28
	s_waitcnt lgkmcnt(2)
	v_mov_b32_e32 v7, v24
	v_fmac_f32_e32 v77, v17, v17
	v_sub_f32_e32 v27, v22, v23
	v_pk_mul_f32 v[22:23], v[168:169], v[6:7]
	v_mov_b32_e32 v168, v29
	v_mov_b32_e32 v7, v25
	v_fmac_f32_e32 v77, v66, v66
	v_sub_f32_e32 v24, v22, v23
	v_pk_mul_f32 v[22:23], v[168:169], v[6:7]
	v_mov_b32_e32 v168, v30
	s_waitcnt lgkmcnt(1)
	v_mov_b32_e32 v7, v48
	v_fmac_f32_e32 v77, v73, v73
	v_sub_f32_e32 v25, v22, v23
	v_pk_mul_f32 v[22:23], v[168:169], v[6:7]
	v_mov_b32_e32 v168, v31
	v_mov_b32_e32 v7, v49
	v_fmac_f32_e32 v77, v74, v74
	v_pk_mul_f32 v[28:29], v[168:169], v[6:7]
	v_fmac_f32_e32 v77, v71, v71
	v_lshlrev_b64 v[48:49], 1, v[4:5]
	v_sub_f32_e32 v22, v22, v23
	v_sub_f32_e32 v23, v28, v29
	s_waitcnt lgkmcnt(0)
	v_pk_mul_f32 v[28:29], v[172:173], v[78:79]
	v_fmac_f32_e32 v77, v72, v72
	v_lshl_add_u64 v[4:5], v[174:175], 0, v[48:49]
	v_pk_fma_f32 v[6:7], v[32:33], v[6:7], v[28:29] op_sel_hi:[1,0,1] neg_lo:[0,0,1] neg_hi:[0,0,1]
	v_fmac_f32_e32 v77, v50, v50
	v_lshlrev_b32_e32 v246, 1, v242
	v_add_u32_e32 v246, 0x22900, v246
	ds_read_b128 v[88:91], v246 offset:0
	ds_read_b128 v[92:95], v246 offset:32
	ds_read_b128 v[96:99], v246 offset:64
	ds_read_b128 v[100:103], v246 offset:96
	ds_read_b128 v[104:107], v246 offset:128
	ds_read_b128 v[108:111], v246 offset:160
	ds_read_b128 v[112:115], v246 offset:192
	ds_read_b128 v[116:119], v246 offset:224
	ds_read_b128 v[120:123], v246 offset:256
	ds_read_b128 v[124:127], v246 offset:288
	ds_read_b128 v[128:131], v246 offset:320
	ds_read_b128 v[132:135], v246 offset:352
	ds_read_b128 v[136:139], v246 offset:384
	ds_read_b128 v[140:143], v246 offset:416
	ds_read_b128 v[144:147], v246 offset:448
	ds_read_b128 v[148:151], v246 offset:480
	v_fmac_f32_e32 v77, v51, v51
	v_fmac_f32_e32 v77, v52, v52
	v_fmac_f32_e32 v77, v53, v53
	v_fmac_f32_e32 v77, v75, v75
	v_fmac_f32_e32 v77, v76, v76
	v_fmac_f32_e32 v77, v58, v58
	v_fmac_f32_e32 v77, v59, v59
	v_fmac_f32_e32 v77, v54, v54
	v_fmac_f32_e32 v77, v55, v55
	v_fmac_f32_e32 v77, v56, v56
	v_fmac_f32_e32 v77, v57, v57
	v_fmac_f32_e32 v77, v62, v62
	v_fmac_f32_e32 v77, v63, v63
	v_fmac_f32_e32 v77, v60, v60
	v_fmac_f32_e32 v77, v61, v61
	v_fmac_f32_e32 v77, v34, v34
	v_fmac_f32_e32 v77, v35, v35
	v_fmac_f32_e32 v77, v36, v36
	v_fmac_f32_e32 v77, v37, v37
	v_fmac_f32_e32 v77, v64, v64
	v_fmac_f32_e32 v77, v65, v65
	v_fmac_f32_e32 v77, v42, v42
	v_fmac_f32_e32 v77, v43, v43
	v_fmac_f32_e32 v77, v38, v38
	v_fmac_f32_e32 v77, v39, v39
	v_fmac_f32_e32 v77, v40, v40
	v_fmac_f32_e32 v77, v41, v41
	v_fmac_f32_e32 v77, v46, v46
	v_fmac_f32_e32 v77, v47, v47
	v_fmac_f32_e32 v77, v44, v44
	v_fmac_f32_e32 v77, v45, v45
	v_fmac_f32_e32 v77, v18, v18
	v_fmac_f32_e32 v77, v19, v19
	v_fmac_f32_e32 v77, v20, v20
	v_sub_f32_e32 v26, v80, v81
	v_fmac_f32_e32 v77, v21, v21
	v_fmac_f32_e32 v77, v26, v26
	v_fmac_f32_e32 v77, v27, v27
	v_fmac_f32_e32 v77, v24, v24
	v_fmac_f32_e32 v77, v25, v25
	v_fmac_f32_e32 v77, v22, v22
	v_pk_mul_f32 v[32:33], v[6:7], v[6:7]
	v_fmac_f32_e32 v77, v23, v23
	v_add_f32_e32 v32, v77, v32
	v_add_f32_e32 v32, v32, v33
	v_mov_b32_e32 v33, v32
	s_waitcnt lgkmcnt(0)
	s_nop 1
	v_permlane32_swap_b32_e32 v33, v32
	v_add_f32_e32 v32, v32, v33
	v_fmamk_f32 v32, v32, 0x3c000000, v214
	v_mul_f32_e32 v33, 0x4f800000, v32
	v_cmp_gt_f32_e32 vcc, s71, v32
	s_nop 1
	v_cndmask_b32_e32 v32, v32, v33, vcc
	v_sqrt_f32_e32 v33, v32
	s_nop 0
	v_add_u32_e32 v77, -1, v33
	v_fma_f32 v80, -v77, v33, v32
	v_cmp_ge_f32_e64 s[4:5], 0, v80
	v_add_u32_e32 v80, 1, v33
	s_nop 0
	v_cndmask_b32_e64 v77, v33, v77, s[4:5]
	v_fma_f32 v33, -v80, v33, v32
	v_cmp_lt_f32_e64 s[4:5], 0, v33
	s_nop 1
	v_cndmask_b32_e64 v33, v77, v80, s[4:5]
	v_mul_f32_e32 v77, 0x37800000, v33
	v_cndmask_b32_e32 v33, v33, v77, vcc
	v_cmp_class_f32_e32 vcc, v32, v200
	s_nop 1
	v_cndmask_b32_e32 v32, v33, v32, vcc
	v_div_scale_f32 v33, s[4:5], v32, v32, s76
	v_rcp_f32_e32 v77, v33
	s_nop 0
	v_fma_f32 v80, -v33, v77, 1.0
	v_fmac_f32_e32 v77, v80, v77
	v_div_scale_f32 v80, vcc, s76, v32, s76
	v_mul_f32_e32 v81, v80, v77
	v_fma_f32 v82, -v33, v81, v80
	v_fmac_f32_e32 v81, v82, v77
	v_fma_f32 v33, -v33, v81, v80
	v_div_fmas_f32 v33, v33, v77, v81
	v_div_fixup_f32 v77, v33, v32, s76
	v_lshl_add_u64 v[244:245], v[176:177], 0, v[48:49]
	v_lshl_add_u64 v[244:245], v[244:245], 0, v[242:243]
	s_waitcnt vmcnt(7)
	v_permlane32_swap_b32_e32 v152, v154
	v_permlane32_swap_b32_e32 v153, v155
	v_mul_f32_e32 v13, v13, v77
	v_mul_f32_e32 v14, v14, v77
	v_lshlrev_b32_e32 v247, 16, v152
	v_mul_f32_e32 v13, v88, v13
	v_mul_f32_e32 v14, v89, v14
	v_and_b32_e32 v152, 0xffff0000, v152
	v_mul_f32_e32 v13, v13, v247
	v_mul_f32_e32 v14, v14, v152
	v_cvt_pk_bf16_f32 v152, v13, v14
	v_mul_f32_e32 v8, v8, v77
	v_mul_f32_e32 v9, v9, v77
	v_lshlrev_b32_e32 v247, 16, v153
	v_mul_f32_e32 v8, v90, v8
	v_mul_f32_e32 v9, v91, v9
	v_and_b32_e32 v153, 0xffff0000, v153
	v_mul_f32_e32 v8, v8, v247
	v_mul_f32_e32 v9, v9, v153
	v_cvt_pk_bf16_f32 v153, v8, v9
	v_mul_f32_e32 v2, v2, v77
	v_mul_f32_e32 v10, v10, v77
	v_lshlrev_b32_e32 v247, 16, v154
	v_mul_f32_e32 v2, v92, v2
	v_mul_f32_e32 v10, v93, v10
	v_and_b32_e32 v154, 0xffff0000, v154
	v_mul_f32_e32 v2, v2, v247
	v_mul_f32_e32 v10, v10, v154
	v_cvt_pk_bf16_f32 v154, v2, v10
	v_mul_f32_e32 v11, v11, v77
	v_mul_f32_e32 v12, v12, v77
	v_lshlrev_b32_e32 v247, 16, v155
	v_mul_f32_e32 v11, v94, v11
	v_mul_f32_e32 v12, v95, v12
	v_and_b32_e32 v155, 0xffff0000, v155
	v_mul_f32_e32 v11, v11, v247
	v_mul_f32_e32 v12, v12, v155
	v_cvt_pk_bf16_f32 v155, v11, v12
	s_nop 1
	v_permlane32_swap_b32_e32 v152, v154
	v_permlane32_swap_b32_e32 v153, v155
	global_store_dwordx4 v[244:245], v[152:155], off offset:0
	s_waitcnt vmcnt(7)
	v_permlane32_swap_b32_e32 v156, v158
	v_permlane32_swap_b32_e32 v157, v159
	v_mul_f32_e32 v69, v69, v77
	v_mul_f32_e32 v70, v70, v77
	v_lshlrev_b32_e32 v247, 16, v156
	v_mul_f32_e32 v69, v96, v69
	v_mul_f32_e32 v70, v97, v70
	v_and_b32_e32 v156, 0xffff0000, v156
	v_mul_f32_e32 v69, v69, v247
	v_mul_f32_e32 v70, v70, v156
	v_cvt_pk_bf16_f32 v156, v69, v70
	v_mul_f32_e32 v67, v67, v77
	v_mul_f32_e32 v68, v68, v77
	v_lshlrev_b32_e32 v247, 16, v157
	v_mul_f32_e32 v67, v98, v67
	v_mul_f32_e32 v68, v99, v68
	v_and_b32_e32 v157, 0xffff0000, v157
	v_mul_f32_e32 v67, v67, v247
	v_mul_f32_e32 v68, v68, v157
	v_cvt_pk_bf16_f32 v157, v67, v68
	v_mul_f32_e32 v15, v15, v77
	v_mul_f32_e32 v16, v16, v77
	v_lshlrev_b32_e32 v247, 16, v158
	v_mul_f32_e32 v15, v100, v15
	v_mul_f32_e32 v16, v101, v16
	v_and_b32_e32 v158, 0xffff0000, v158
	v_mul_f32_e32 v15, v15, v247
	v_mul_f32_e32 v16, v16, v158
	v_cvt_pk_bf16_f32 v158, v15, v16
	v_mul_f32_e32 v17, v17, v77
	v_mul_f32_e32 v66, v66, v77
	v_lshlrev_b32_e32 v247, 16, v159
	v_mul_f32_e32 v17, v102, v17
	v_mul_f32_e32 v66, v103, v66
	v_and_b32_e32 v159, 0xffff0000, v159
	v_mul_f32_e32 v17, v17, v247
	v_mul_f32_e32 v66, v66, v159
	v_cvt_pk_bf16_f32 v159, v17, v66
	s_nop 1
	v_permlane32_swap_b32_e32 v156, v158
	v_permlane32_swap_b32_e32 v157, v159
	global_store_dwordx4 v[244:245], v[156:159], off offset:32
	s_waitcnt vmcnt(7)
	v_permlane32_swap_b32_e32 v160, v162
	v_permlane32_swap_b32_e32 v161, v163
	v_mul_f32_e32 v73, v73, v77
	v_mul_f32_e32 v74, v74, v77
	v_lshlrev_b32_e32 v247, 16, v160
	v_mul_f32_e32 v73, v104, v73
	v_mul_f32_e32 v74, v105, v74
	v_and_b32_e32 v160, 0xffff0000, v160
	v_mul_f32_e32 v73, v73, v247
	v_mul_f32_e32 v74, v74, v160
	v_cvt_pk_bf16_f32 v160, v73, v74
	v_mul_f32_e32 v71, v71, v77
	v_mul_f32_e32 v72, v72, v77
	v_lshlrev_b32_e32 v247, 16, v161
	v_mul_f32_e32 v71, v106, v71
	v_mul_f32_e32 v72, v107, v72
	v_and_b32_e32 v161, 0xffff0000, v161
	v_mul_f32_e32 v71, v71, v247
	v_mul_f32_e32 v72, v72, v161
	v_cvt_pk_bf16_f32 v161, v71, v72
	v_mul_f32_e32 v50, v50, v77
	v_mul_f32_e32 v51, v51, v77
	v_lshlrev_b32_e32 v247, 16, v162
	v_mul_f32_e32 v50, v108, v50
	v_mul_f32_e32 v51, v109, v51
	v_and_b32_e32 v162, 0xffff0000, v162
	v_mul_f32_e32 v50, v50, v247
	v_mul_f32_e32 v51, v51, v162
	v_cvt_pk_bf16_f32 v162, v50, v51
	v_mul_f32_e32 v52, v52, v77
	v_mul_f32_e32 v53, v53, v77
	v_lshlrev_b32_e32 v247, 16, v163
	v_mul_f32_e32 v52, v110, v52
	v_mul_f32_e32 v53, v111, v53
	v_and_b32_e32 v163, 0xffff0000, v163
	v_mul_f32_e32 v52, v52, v247
	v_mul_f32_e32 v53, v53, v163
	v_cvt_pk_bf16_f32 v163, v52, v53
	s_nop 1
	v_permlane32_swap_b32_e32 v160, v162
	v_permlane32_swap_b32_e32 v161, v163
	global_store_dwordx4 v[244:245], v[160:163], off offset:64
	s_waitcnt vmcnt(7)
	v_permlane32_swap_b32_e32 v220, v222
	v_permlane32_swap_b32_e32 v221, v223
	v_mul_f32_e32 v75, v75, v77
	v_mul_f32_e32 v76, v76, v77
	v_lshlrev_b32_e32 v247, 16, v220
	v_mul_f32_e32 v75, v112, v75
	v_mul_f32_e32 v76, v113, v76
	v_and_b32_e32 v220, 0xffff0000, v220
	v_mul_f32_e32 v75, v75, v247
	v_mul_f32_e32 v76, v76, v220
	v_cvt_pk_bf16_f32 v220, v75, v76
	v_mul_f32_e32 v58, v58, v77
	v_mul_f32_e32 v59, v59, v77
	v_lshlrev_b32_e32 v247, 16, v221
	v_mul_f32_e32 v58, v114, v58
	v_mul_f32_e32 v59, v115, v59
	v_and_b32_e32 v221, 0xffff0000, v221
	v_mul_f32_e32 v58, v58, v247
	v_mul_f32_e32 v59, v59, v221
	v_cvt_pk_bf16_f32 v221, v58, v59
	v_mul_f32_e32 v54, v54, v77
	v_mul_f32_e32 v55, v55, v77
	v_lshlrev_b32_e32 v247, 16, v222
	v_mul_f32_e32 v54, v116, v54
	v_mul_f32_e32 v55, v117, v55
	v_and_b32_e32 v222, 0xffff0000, v222
	v_mul_f32_e32 v54, v54, v247
	v_mul_f32_e32 v55, v55, v222
	v_cvt_pk_bf16_f32 v222, v54, v55
	v_mul_f32_e32 v56, v56, v77
	v_mul_f32_e32 v57, v57, v77
	v_lshlrev_b32_e32 v247, 16, v223
	v_mul_f32_e32 v56, v118, v56
	v_mul_f32_e32 v57, v119, v57
	v_and_b32_e32 v223, 0xffff0000, v223
	v_mul_f32_e32 v56, v56, v247
	v_mul_f32_e32 v57, v57, v223
	v_cvt_pk_bf16_f32 v223, v56, v57
	s_nop 1
	v_permlane32_swap_b32_e32 v220, v222
	v_permlane32_swap_b32_e32 v221, v223
	global_store_dwordx4 v[244:245], v[220:223], off offset:96
	s_waitcnt vmcnt(7)
	v_permlane32_swap_b32_e32 v224, v226
	v_permlane32_swap_b32_e32 v225, v227
	v_mul_f32_e32 v62, v62, v77
	v_mul_f32_e32 v63, v63, v77
	v_lshlrev_b32_e32 v247, 16, v224
	v_mul_f32_e32 v62, v120, v62
	v_mul_f32_e32 v63, v121, v63
	v_and_b32_e32 v224, 0xffff0000, v224
	v_mul_f32_e32 v62, v62, v247
	v_mul_f32_e32 v63, v63, v224
	v_cvt_pk_bf16_f32 v224, v62, v63
	v_mul_f32_e32 v60, v60, v77
	v_mul_f32_e32 v61, v61, v77
	v_lshlrev_b32_e32 v247, 16, v225
	v_mul_f32_e32 v60, v122, v60
	v_mul_f32_e32 v61, v123, v61
	v_and_b32_e32 v225, 0xffff0000, v225
	v_mul_f32_e32 v60, v60, v247
	v_mul_f32_e32 v61, v61, v225
	v_cvt_pk_bf16_f32 v225, v60, v61
	v_mul_f32_e32 v34, v34, v77
	v_mul_f32_e32 v35, v35, v77
	v_lshlrev_b32_e32 v247, 16, v226
	v_mul_f32_e32 v34, v124, v34
	v_mul_f32_e32 v35, v125, v35
	v_and_b32_e32 v226, 0xffff0000, v226
	v_mul_f32_e32 v34, v34, v247
	v_mul_f32_e32 v35, v35, v226
	v_cvt_pk_bf16_f32 v226, v34, v35
	v_mul_f32_e32 v36, v36, v77
	v_mul_f32_e32 v37, v37, v77
	v_lshlrev_b32_e32 v247, 16, v227
	v_mul_f32_e32 v36, v126, v36
	v_mul_f32_e32 v37, v127, v37
	v_and_b32_e32 v227, 0xffff0000, v227
	v_mul_f32_e32 v36, v36, v247
	v_mul_f32_e32 v37, v37, v227
	v_cvt_pk_bf16_f32 v227, v36, v37
	s_nop 1
	v_permlane32_swap_b32_e32 v224, v226
	v_permlane32_swap_b32_e32 v225, v227
	global_store_dwordx4 v[244:245], v[224:227], off offset:128
	s_waitcnt vmcnt(7)
	v_permlane32_swap_b32_e32 v228, v230
	v_permlane32_swap_b32_e32 v229, v231
	v_mul_f32_e32 v64, v64, v77
	v_mul_f32_e32 v65, v65, v77
	v_lshlrev_b32_e32 v247, 16, v228
	v_mul_f32_e32 v64, v128, v64
	v_mul_f32_e32 v65, v129, v65
	v_and_b32_e32 v228, 0xffff0000, v228
	v_mul_f32_e32 v64, v64, v247
	v_mul_f32_e32 v65, v65, v228
	v_cvt_pk_bf16_f32 v228, v64, v65
	v_mul_f32_e32 v42, v42, v77
	v_mul_f32_e32 v43, v43, v77
	v_lshlrev_b32_e32 v247, 16, v229
	v_mul_f32_e32 v42, v130, v42
	v_mul_f32_e32 v43, v131, v43
	v_and_b32_e32 v229, 0xffff0000, v229
	v_mul_f32_e32 v42, v42, v247
	v_mul_f32_e32 v43, v43, v229
	v_cvt_pk_bf16_f32 v229, v42, v43
	v_mul_f32_e32 v38, v38, v77
	v_mul_f32_e32 v39, v39, v77
	v_lshlrev_b32_e32 v247, 16, v230
	v_mul_f32_e32 v38, v132, v38
	v_mul_f32_e32 v39, v133, v39
	v_and_b32_e32 v230, 0xffff0000, v230
	v_mul_f32_e32 v38, v38, v247
	v_mul_f32_e32 v39, v39, v230
	v_cvt_pk_bf16_f32 v230, v38, v39
	v_mul_f32_e32 v40, v40, v77
	v_mul_f32_e32 v41, v41, v77
	v_lshlrev_b32_e32 v247, 16, v231
	v_mul_f32_e32 v40, v134, v40
	v_mul_f32_e32 v41, v135, v41
	v_and_b32_e32 v231, 0xffff0000, v231
	v_mul_f32_e32 v40, v40, v247
	v_mul_f32_e32 v41, v41, v231
	v_cvt_pk_bf16_f32 v231, v40, v41
	s_nop 1
	v_permlane32_swap_b32_e32 v228, v230
	v_permlane32_swap_b32_e32 v229, v231
	global_store_dwordx4 v[244:245], v[228:231], off offset:160
	s_waitcnt vmcnt(7)
	v_permlane32_swap_b32_e32 v232, v234
	v_permlane32_swap_b32_e32 v233, v235
	v_mul_f32_e32 v46, v46, v77
	v_mul_f32_e32 v47, v47, v77
	v_lshlrev_b32_e32 v247, 16, v232
	v_mul_f32_e32 v46, v136, v46
	v_mul_f32_e32 v47, v137, v47
	v_and_b32_e32 v232, 0xffff0000, v232
	v_mul_f32_e32 v46, v46, v247
	v_mul_f32_e32 v47, v47, v232
	v_cvt_pk_bf16_f32 v232, v46, v47
	v_mul_f32_e32 v44, v44, v77
	v_mul_f32_e32 v45, v45, v77
	v_lshlrev_b32_e32 v247, 16, v233
	v_mul_f32_e32 v44, v138, v44
	v_mul_f32_e32 v45, v139, v45
	v_and_b32_e32 v233, 0xffff0000, v233
	v_mul_f32_e32 v44, v44, v247
	v_mul_f32_e32 v45, v45, v233
	v_cvt_pk_bf16_f32 v233, v44, v45
	v_mul_f32_e32 v18, v18, v77
	v_mul_f32_e32 v19, v19, v77
	v_lshlrev_b32_e32 v247, 16, v234
	v_mul_f32_e32 v18, v140, v18
	v_mul_f32_e32 v19, v141, v19
	v_and_b32_e32 v234, 0xffff0000, v234
	v_mul_f32_e32 v18, v18, v247
	v_mul_f32_e32 v19, v19, v234
	v_cvt_pk_bf16_f32 v234, v18, v19
	v_mul_f32_e32 v20, v20, v77
	v_mul_f32_e32 v21, v21, v77
	v_lshlrev_b32_e32 v247, 16, v235
	v_mul_f32_e32 v20, v142, v20
	v_mul_f32_e32 v21, v143, v21
	v_and_b32_e32 v235, 0xffff0000, v235
	v_mul_f32_e32 v20, v20, v247
	v_mul_f32_e32 v21, v21, v235
	v_cvt_pk_bf16_f32 v235, v20, v21
	s_nop 1
	v_permlane32_swap_b32_e32 v232, v234
	v_permlane32_swap_b32_e32 v233, v235
	global_store_dwordx4 v[244:245], v[232:235], off offset:192
	s_waitcnt vmcnt(7)
	v_permlane32_swap_b32_e32 v236, v238
	v_permlane32_swap_b32_e32 v237, v239
	v_mul_f32_e32 v26, v26, v77
	v_mul_f32_e32 v27, v27, v77
	v_lshlrev_b32_e32 v247, 16, v236
	v_mul_f32_e32 v26, v144, v26
	v_mul_f32_e32 v27, v145, v27
	v_and_b32_e32 v236, 0xffff0000, v236
	v_mul_f32_e32 v26, v26, v247
	v_mul_f32_e32 v27, v27, v236
	v_cvt_pk_bf16_f32 v236, v26, v27
	v_mul_f32_e32 v24, v24, v77
	v_mul_f32_e32 v25, v25, v77
	v_lshlrev_b32_e32 v247, 16, v237
	v_mul_f32_e32 v24, v146, v24
	v_mul_f32_e32 v25, v147, v25
	v_and_b32_e32 v237, 0xffff0000, v237
	v_mul_f32_e32 v24, v24, v247
	v_mul_f32_e32 v25, v25, v237
	v_cvt_pk_bf16_f32 v237, v24, v25
	v_mul_f32_e32 v22, v22, v77
	v_mul_f32_e32 v23, v23, v77
	v_lshlrev_b32_e32 v247, 16, v238
	v_mul_f32_e32 v22, v148, v22
	v_mul_f32_e32 v23, v149, v23
	v_and_b32_e32 v238, 0xffff0000, v238
	v_mul_f32_e32 v22, v22, v247
	v_mul_f32_e32 v23, v23, v238
	v_cvt_pk_bf16_f32 v238, v22, v23
	v_mul_f32_e32 v6, v6, v77
	v_mul_f32_e32 v7, v7, v77
	v_lshlrev_b32_e32 v247, 16, v239
	v_mul_f32_e32 v6, v150, v6
	v_mul_f32_e32 v7, v151, v7
	v_and_b32_e32 v239, 0xffff0000, v239
	v_mul_f32_e32 v6, v6, v247
	v_mul_f32_e32 v7, v7, v239
	v_cvt_pk_bf16_f32 v239, v6, v7
	s_nop 1
	v_permlane32_swap_b32_e32 v236, v238
	v_permlane32_swap_b32_e32 v237, v239
	global_store_dwordx4 v[244:245], v[236:239], off offset:224
